# gating phase: V/W tile loads issued before the rstd barrier (barrier moved after load issue, no vmcnt drain)
# speedup vs baseline: 1.0064x; 1.0020x over previous
.LBB0_2542:
	s_or_b64 exec, exec, s[34:35]
	s_and_b32 s12, s31, 0x380
	v_add_u32_e32 v4, s38, v55
	s_lshl_b32 s34, s12, 1
	s_mov_b32 s35, s13
	v_ashrrev_i32_e32 v5, 31, v4
	v_lshl_add_u64 v[16:17], v[42:43], 0, s[34:35]
	v_lshlrev_b64 v[4:5], 11, v[4:5]
	v_lshl_add_u64 v[4:5], v[16:17], 0, v[4:5]
	global_load_dwordx4 v[4:7], v[4:5], off
	v_add_u32_e32 v8, s38, v57
	v_ashrrev_i32_e32 v9, 31, v8
	v_lshlrev_b64 v[8:9], 11, v[8:9]
	v_lshl_add_u64 v[8:9], v[16:17], 0, v[8:9]
	global_load_dwordx4 v[8:11], v[8:9], off
	v_add_u32_e32 v12, s38, v59
	v_ashrrev_i32_e32 v13, 31, v12
	v_lshlrev_b64 v[12:13], 11, v[12:13]
	v_lshl_add_u64 v[12:13], v[16:17], 0, v[12:13]
	global_load_dwordx4 v[12:15], v[12:13], off
	v_add_u32_e32 v18, s38, v61
	v_ashrrev_i32_e32 v19, 31, v18
	v_lshlrev_b64 v[18:19], 11, v[18:19]
	v_lshl_add_u64 v[16:17], v[16:17], 0, v[18:19]
	global_load_dwordx4 v[16:19], v[16:17], off
	v_lshl_add_u64 v[20:21], v[44:45], 0, s[12:13]
	v_lshlrev_b64 v[20:21], 8, v[20:21]
	v_lshl_add_u64 v[52:53], v[46:47], 0, v[20:21]
	global_load_dwordx4 v[112:115], v[52:53], off
	global_load_dwordx4 v[116:119], v[52:53], off offset:64
	global_load_dwordx4 v[120:123], v[52:53], off offset:128
	global_load_dwordx4 v[124:127], v[52:53], off offset:192
	s_waitcnt lgkmcnt(0)
	s_barrier
	ds_read_b32 v2, v56 offset:34816
	v_mov_b32_e32 v36, 0
	v_mov_b32_e32 v37, 0
	v_mov_b32_e32 v38, 0
	v_mov_b32_e32 v39, 0
	s_andn2_b64 vcc, exec, s[24:25]
	v_mov_b32_e32 v34, 0
	v_mov_b32_e32 v35, 0
	s_waitcnt vmcnt(7)
	v_lshlrev_b32_e32 v20, 16, v4
	v_and_b32_e32 v21, 0xffff0000, v4
	v_lshlrev_b32_e32 v4, 16, v5
	v_and_b32_e32 v5, 0xffff0000, v5
	v_lshlrev_b32_e32 v22, 16, v6
	v_and_b32_e32 v23, 0xffff0000, v6
	v_lshlrev_b32_e32 v6, 16, v7
	v_and_b32_e32 v7, 0xffff0000, v7
	s_waitcnt lgkmcnt(0)
	v_pk_mul_f32 v[20:21], v[2:3], v[20:21] op_sel_hi:[0,1]
	v_pk_mul_f32 v[30:31], v[2:3], v[4:5] op_sel_hi:[0,1]
	v_pk_mul_f32 v[22:23], v[2:3], v[22:23] op_sel_hi:[0,1]
	v_pk_mul_f32 v[32:33], v[2:3], v[6:7] op_sel_hi:[0,1]
	v_cvt_pk_bf16_f32 v4, v20, v21
	v_cvt_pk_bf16_f32 v5, v30, v31
	v_cvt_pk_bf16_f32 v6, v22, v23
	v_cvt_pk_bf16_f32 v7, v32, v33
	ds_write_b128 v64, v[4:7]
	ds_read_b32 v2, v58 offset:34816
	s_waitcnt vmcnt(6)
	v_lshlrev_b32_e32 v24, 16, v8
	v_and_b32_e32 v25, 0xffff0000, v8
	v_lshlrev_b32_e32 v8, 16, v9
	v_and_b32_e32 v9, 0xffff0000, v9
	v_lshlrev_b32_e32 v26, 16, v10
	v_and_b32_e32 v27, 0xffff0000, v10
	v_lshlrev_b32_e32 v10, 16, v11
	v_and_b32_e32 v11, 0xffff0000, v11
	s_waitcnt lgkmcnt(0)
	v_pk_mul_f32 v[4:5], v[2:3], v[24:25] op_sel_hi:[0,1]
	v_pk_mul_f32 v[6:7], v[2:3], v[8:9] op_sel_hi:[0,1]
	v_pk_mul_f32 v[8:9], v[2:3], v[26:27] op_sel_hi:[0,1]
	v_pk_mul_f32 v[10:11], v[2:3], v[10:11] op_sel_hi:[0,1]
	v_cvt_pk_bf16_f32 v4, v4, v5
	v_cvt_pk_bf16_f32 v5, v6, v7
	v_cvt_pk_bf16_f32 v6, v8, v9
	v_cvt_pk_bf16_f32 v7, v10, v11
	ds_write_b128 v65, v[4:7]
	ds_read_b32 v2, v60 offset:34816
	s_waitcnt vmcnt(5)
	v_lshlrev_b32_e32 v28, 16, v12
	v_and_b32_e32 v29, 0xffff0000, v12
	v_lshlrev_b32_e32 v12, 16, v13
	v_and_b32_e32 v13, 0xffff0000, v13
	v_lshlrev_b32_e32 v20, 16, v14
	v_and_b32_e32 v21, 0xffff0000, v14
	v_lshlrev_b32_e32 v14, 16, v15
	v_and_b32_e32 v15, 0xffff0000, v15
	s_waitcnt lgkmcnt(0)
	v_pk_mul_f32 v[4:5], v[2:3], v[28:29] op_sel_hi:[0,1]
	v_pk_mul_f32 v[6:7], v[2:3], v[12:13] op_sel_hi:[0,1]
	v_pk_mul_f32 v[12:13], v[2:3], v[20:21] op_sel_hi:[0,1]
	v_pk_mul_f32 v[14:15], v[2:3], v[14:15] op_sel_hi:[0,1]
	v_cvt_pk_bf16_f32 v4, v4, v5
	v_cvt_pk_bf16_f32 v5, v6, v7
	v_cvt_pk_bf16_f32 v6, v12, v13
	v_cvt_pk_bf16_f32 v7, v14, v15
	ds_write_b128 v66, v[4:7]
	ds_read_b32 v2, v62 offset:34816
	s_waitcnt vmcnt(4)
	v_lshlrev_b32_e32 v8, 16, v16
	v_and_b32_e32 v9, 0xffff0000, v16
	v_lshlrev_b32_e32 v10, 16, v17
	v_and_b32_e32 v11, 0xffff0000, v17
	v_lshlrev_b32_e32 v4, 16, v18
	v_and_b32_e32 v5, 0xffff0000, v18
	v_lshlrev_b32_e32 v6, 16, v19
	v_and_b32_e32 v7, 0xffff0000, v19
	s_waitcnt lgkmcnt(0)
	v_pk_mul_f32 v[8:9], v[2:3], v[8:9] op_sel_hi:[0,1]
	v_pk_mul_f32 v[10:11], v[2:3], v[10:11] op_sel_hi:[0,1]
	v_pk_mul_f32 v[12:13], v[2:3], v[4:5] op_sel_hi:[0,1]
	v_pk_mul_f32 v[14:15], v[2:3], v[6:7] op_sel_hi:[0,1]
	v_cvt_pk_bf16_f32 v4, v8, v9
	v_cvt_pk_bf16_f32 v5, v10, v11
	v_cvt_pk_bf16_f32 v6, v12, v13
	v_cvt_pk_bf16_f32 v7, v14, v15
	ds_write_b128 v67, v[4:7]
	v_mov_b32_e32 v28, 0
	v_mov_b32_e32 v29, 0
	v_mov_b32_e32 v30, 0
	v_mov_b32_e32 v31, 0
	v_mov_b32_e32 v24, 0
	v_mov_b32_e32 v25, 0
	v_mov_b32_e32 v26, 0
	v_mov_b32_e32 v27, 0
	v_mov_b32_e32 v20, 0
	v_mov_b32_e32 v21, 0
	v_mov_b32_e32 v22, 0
	v_mov_b32_e32 v23, 0
	v_mov_b32_e32 v12, 0
	v_mov_b32_e32 v13, 0
	v_mov_b32_e32 v14, 0
	v_mov_b32_e32 v15, 0
	v_mov_b32_e32 v16, 0
	v_mov_b32_e32 v17, 0
	v_mov_b32_e32 v18, 0
	v_mov_b32_e32 v19, 0
	v_mov_b32_e32 v8, 0
	v_mov_b32_e32 v9, 0
	v_mov_b32_e32 v10, 0
	v_mov_b32_e32 v11, 0
	v_mov_b32_e32 v4, 0
	v_mov_b32_e32 v5, 0
	v_mov_b32_e32 v6, 0
	v_mov_b32_e32 v7, 0
	v_mov_b32_e32 v32, 0
	v_mov_b32_e32 v33, 0
	s_waitcnt lgkmcnt(0)
	s_barrier
	s_cbranch_vccnz .LBB0_2546
	ds_read_b64_tr_b16 v[4:5], v63
	ds_read_b64_tr_b16 v[6:7], v63 offset:1088
	ds_read_b64_tr_b16 v[10:11], v63 offset:1120
	ds_read_b64_tr_b16 v[8:9], v63 offset:32
	ds_read_b64_tr_b16 v[12:13], v63 offset:64
	ds_read_b64_tr_b16 v[16:17], v63 offset:96
	ds_read_b64_tr_b16 v[14:15], v63 offset:1152
	ds_read_b64_tr_b16 v[18:19], v63 offset:1184
	s_waitcnt vmcnt(0) lgkmcnt(6)
	v_mfma_f32_16x16x32_bf16 v[28:31], v[4:7], v[112:115], 0
	ds_read_b64_tr_b16 v[4:5], v63 offset:128
	s_waitcnt lgkmcnt(5)
	v_mfma_f32_16x16x32_bf16 v[24:27], v[8:11], v[112:115], 0
	ds_read_b64_tr_b16 v[6:7], v63 offset:1216
	ds_read_b64_tr_b16 v[10:11], v63 offset:1248
	ds_read_b64_tr_b16 v[8:9], v63 offset:160
	ds_read_b64_tr_b16 v[36:37], v63 offset:192
	ds_read_b64_tr_b16 v[68:69], v63 offset:224
	ds_read_b64_tr_b16 v[38:39], v63 offset:1280
	ds_read_b64_tr_b16 v[70:71], v63 offset:1312
	s_waitcnt lgkmcnt(9)
	v_mfma_f32_16x16x32_bf16 v[20:23], v[12:15], v[112:115], 0
	s_waitcnt lgkmcnt(8)
	v_mfma_f32_16x16x32_bf16 v[12:15], v[16:19], v[112:115], 0
	s_waitcnt lgkmcnt(6)
	v_mfma_f32_16x16x32_bf16 v[16:19], v[4:7], v[112:115], 0
	s_waitcnt lgkmcnt(1)
	v_mfma_f32_16x16x32_bf16 v[4:7], v[36:39], v[112:115], 0
	s_waitcnt lgkmcnt(0)
	v_mfma_f32_16x16x32_bf16 v[36:39], v[68:71], v[112:115], 0
	v_mfma_f32_16x16x32_bf16 v[8:11], v[8:11], v[112:115], 0
	s_nop 6
	v_mov_b32_e32 v32, v36
	v_mov_b32_e32 v33, v37
	v_mov_b32_e32 v34, v38
	v_mov_b32_e32 v35, v39
	s_andn2_b64 vcc, exec, s[26:27]
	s_cbranch_vccz .LBB0_2547
